# in_proj phase thin_gemm units moved off the 32 workgroups that own the sixth tile
# speedup vs baseline: 1.0025x; 1.0025x over previous
.LBB0_687:
	s_waitcnt vmcnt(0)
	v_mov_b32_e32 v0, v177
	v_readlane_b32 s0, v254, 0
	s_mov_b32 s99, s29
	s_cmpk_eq_i32 s29, 0x100
	s_cbranch_scc0 .Lthin_nomap
	v_readlane_b32 s98, v255, 30
	s_nop 3
	s_mov_b32 s101, 0
	s_cmp_eq_u32 s98, 1
	s_cselect_b32 s101, 32, s101
	s_cmp_eq_u32 s98, 11
	s_cselect_b32 s101, 0x80, s101
	s_cmp_eq_u32 s98, 16
	s_cselect_b32 s101, 0x80, s101
	s_sub_u32 s99, 0x100, s101
	s_sub_i32 s0, s0, s101
	s_cmp_lt_i32 s0, 0
	s_cbranch_scc1 .LBB0_718
